# work balance: third-round prep units, fifth-round conv units (layer 0) and ctx diff units moved onto disjoint workgroups
# speedup vs baseline: 1.0082x; 1.0080x over previous
.LBB0_666:
	v_mov_b32_e32 v108, v1
	s_cmpk_gt_i32 s96, 0x207
	v_readfirstlane_b32 s24, v108
	s_cbranch_scc1 .LBB0_698
	s_add_u32 s0, s88, 0x9b00000
	s_addc_u32 s1, s89, 0
	s_add_u32 s8, s88, 0x180000
	v_mbcnt_lo_u32_b32 v2, -1, 0
	s_addc_u32 s9, s89, 0
	s_mov_b32 s11, 0
	v_mov_b32_e32 v19, 0
	s_movk_i32 s3, 0x1640
	v_mov_b64_e32 v[20:21], s[0:1]
	s_mov_b32 s25, 0xffff0000
	s_mov_b64 s[12:13], 0x4000
	s_movk_i32 s26, 0x4000
	s_movk_i32 s27, 0x7fff
	v_mbcnt_hi_u32_b32 v62, -1, v2
	s_movk_i32 s28, 0x800
	s_mov_b32 s29, 0x8200
	s_movk_i32 s30, 0x1040
	s_movk_i32 s31, 0x210
	s_movk_i32 s33, 0x5ff
	s_mov_b32 s34, 0x15000000
	s_lshr_b32 s35, s96, 2
	s_and_b32 s98, s96, 3
	s_lshl_b32 s98, s98, 6
	s_or_b32 s35, s35, s98
	s_xor_b32 s35, s35, 0x40
	s_branch .LBB0_669

.LBB0_720:
	s_cmpk_gt_i32 s96, 0x40f
	s_barrier
	s_cbranch_scc1 .LBB0_755
	v_and_b32_e32 v2, 15, v108
	v_lshl_or_b32 v34, s3, 5, v2
	v_and_b32_e32 v74, 48, v108
	v_mov_b32_e32 v75, 0
	v_lshl_add_u64 v[2:3], s[88:89], 0, v[74:75]
	s_mov_b64 s[0:1], 0x400000
	v_ashrrev_i32_e32 v35, 31, v34
	v_lshl_add_u64 v[36:37], v[2:3], 0, s[0:1]
	v_lshlrev_b64 v[2:3], 9, v[34:35]
	v_or_b32_e32 v34, 16, v34
	v_ashrrev_i32_e32 v35, 31, v34
	v_lshlrev_b64 v[34:35], 9, v[34:35]
	v_lshl_add_u64 v[30:31], v[36:37], 0, v[2:3]
	v_lshl_add_u64 v[62:63], v[36:37], 0, v[34:35]
	global_load_dwordx4 v[2:5], v[30:31], off
	global_load_dwordx4 v[6:9], v[30:31], off offset:64
	global_load_dwordx4 v[10:13], v[30:31], off offset:128
	global_load_dwordx4 v[14:17], v[30:31], off offset:192
	global_load_dwordx4 v[18:21], v[30:31], off offset:256
	global_load_dwordx4 v[22:25], v[30:31], off offset:320
	global_load_dwordx4 v[26:29], v[30:31], off offset:384
	s_nop 0
	global_load_dwordx4 v[30:33], v[30:31], off offset:448
	s_nop 0
	global_load_dwordx4 v[34:37], v[62:63], off
	global_load_dwordx4 v[38:41], v[62:63], off offset:64
	global_load_dwordx4 v[42:45], v[62:63], off offset:128
	global_load_dwordx4 v[46:49], v[62:63], off offset:192
	global_load_dwordx4 v[50:53], v[62:63], off offset:256
	global_load_dwordx4 v[54:57], v[62:63], off offset:320
	global_load_dwordx4 v[58:61], v[62:63], off offset:384
	s_nop 0
	global_load_dwordx4 v[62:65], v[62:63], off offset:448
	s_lshl_b32 s3, s96, 5
	s_lshl_b32 s26, s68, 5
	s_movk_i32 s27, 0x4000
	s_movk_i32 s28, 0x1640
	s_movk_i32 s29, 0x780
	s_movk_i32 s30, 0x580
	s_movk_i32 s31, 0x380
	s_movk_i32 s33, 0x180
	s_add_i32 s34, 0, 0x10000
	s_add_i32 s35, 0, 0x18000
	v_mov_b32_e32 v111, 0x3727c5ac
	s_mov_b32 s36, 0x800000
	s_movk_i32 s37, 0x7fff
	s_movk_i32 s38, 0x840
	s_movk_i32 s39, 0x210
	s_mov_b64 s[0:1], 0x5a00600
	v_mov_b32_e32 v112, 1
	s_lshr_b32 s40, s96, 2
	s_and_b32 s98, s96, 3
	s_lshl_b32 s98, s98, 6
	s_or_b32 s40, s40, s98
	s_xor_b32 s40, s40, 0x80
	s_lshl_b32 s3, s40, 5
	s_branch .LBB0_723

.LBB0_930:
	s_cmpk_lt_i32 s96, 0xf8
	s_cbranch_scc1 .LBB0_939
	s_add_u32 s0, s88, 0x9b00000
	v_mbcnt_lo_u32_b32 v2, -1, 0
	s_addc_u32 s1, s89, 0
	v_mbcnt_hi_u32_b32 v152, -1, v2
	s_add_u32 s3, s88, 0x15000000
	s_mov_b32 s4, 0x3f803f80
	v_and_b32_e32 v2, 64, v152
	s_addc_u32 s11, s89, 0
	s_mov_b32 s9, 0
	s_movk_i32 s15, 0x1640
	v_mov_b64_e32 v[134:135], s[0:1]
	v_mov_b32_e32 v137, 0
	s_mov_b32 s10, 0x3e8293ee
	s_movk_i32 s18, 0x7fff
	s_mov_b32 s19, 0xf800000
	v_mov_b32_e32 v139, 0x260
	s_mov_b32 s20, 0x8200
	s_movk_i32 s21, 0x48
	s_mov_b32 s22, 0x7060302
	s_mov_b32 s5, s4
	s_mov_b32 s6, s4
	s_mov_b32 s7, s4
	s_mov_b32 s23, 0x3fb8aa3b
	s_mov_b32 s24, 0xc2ce8ed0
	s_mov_b32 s25, 0x42b17218
	s_mov_b64 s[12:13], 0x5a00400
	s_mov_b32 s14, 0x3c800000
	s_mov_b32 s26, 0x800000
	s_mov_b32 s27, 0x5a00000
	v_xor_b32_e32 v153, 16, v152
	v_add_u32_e32 v154, 64, v2
	v_xor_b32_e32 v155, 32, v152
	v_mov_b32_e32 v156, 1
	v_mov_b32_e32 v157, 0x7f800000
	v_mov_b32_e32 v138, 0x358637bd
	s_add_i32 s28, s96, 0xffffff08
	s_branch .LBB0_933

.LBB0_1908:
	v_mov_b32_e32 v108, v1
	s_cmpk_gt_i32 s96, 0x207
	v_readfirstlane_b32 s27, v108
	s_cbranch_scc1 .LBB0_1940
	s_add_u32 s0, s88, 0x9b00000
	s_addc_u32 s1, s89, 0
	s_add_u32 s8, s88, 0x180000
	v_mbcnt_lo_u32_b32 v2, -1, 0
	s_addc_u32 s9, s89, 0
	s_mov_b32 s11, 0
	v_mov_b32_e32 v19, 0
	s_movk_i32 s3, 0x1640
	v_mov_b64_e32 v[20:21], s[0:1]
	s_mov_b32 s24, 0xffff0000
	s_mov_b64 s[12:13], 0x4000
	s_movk_i32 s25, 0x4000
	s_movk_i32 s26, 0x7fff
	v_mbcnt_hi_u32_b32 v62, -1, v2
	s_movk_i32 s28, 0x800
	s_mov_b32 s29, 0x8200
	s_movk_i32 s30, 0x1040
	s_movk_i32 s31, 0x210
	s_movk_i32 s33, 0x5ff
	s_mov_b32 s34, 0x15000000
	s_lshr_b32 s35, s96, 2
	s_and_b32 s98, s96, 3
	s_lshl_b32 s98, s98, 6
	s_or_b32 s35, s35, s98
	s_xor_b32 s35, s35, 0x40
	s_branch .LBB0_1911
